# all elementwise phases newest-first (E1 l>0 and final flipped too) on top of v006
# baseline (speedup 1.0000x reference)
; template <int x_mode_in>
; __device__ __forceinline__ void phase_elem(const Params& p, bool prev, bool has_y, int l_res, int jg, int ngi_res, int x_mode_out, bool write_h, int l_h, int jsh, int ngi_h) {
;     ...
;         const int pos = prev ? 383 - (b >> 4) : (b >> 4), pmo = 48 * ((pos & 63) >> 3) + 8 * (pos >> 6) + (pos & 7);
;         const int tok0 = pmo * 256 + (b & 15) * 16, s = seq_of(tok0);
;         f32x4 ar[2][2], ah[2][2], sh[2][2];
; #pragma unroll
;         for (int j = 0; j < 2; ++j)
; #pragma unroll
;             for (int k = 0; k < 2; ++k) { ar[j][k] = (f32x4){0.f, 0.f, 0.f, 0.f}; ah[j][k] = ar[j][k]; sh[j][k] = ar[j][k]; }
;         if (has_y) { const float* gp = mod + (((size_t)s * 4 + l_res) * 6 + jg) * 1024 + 8 * lane; const float* np = norm_g + (l_res * 4 + ngi_res) * 1024 + 8 * lane;
; #pragma unroll
;             for (int j = 0; j < 2; ++j)
; #pragma unroll
;                 for (int k = 0; k < 2; ++k) ar[j][k] = *(const f32x4*)(gp + 512 * j + 4 * k) * *(const f32x4*)(np + 512 * j + 4 * k); }
;         if (write_h) { const float* shp = mod + (((size_t)s * 4 + l_h) * 6 + jsh) * 1024 + 8 * lane; const float* scp = shp + 1024; const float* np = norm_g + (l_h * 4 + ngi_h) * 1024 + 8 * lane;
; #pragma unroll
;             for (int j = 0; j < 2; ++j)
; #pragma unroll
;                 for (int k = 0; k < 2; ++k) { ah[j][k] = *(const f32x4*)(np + 512 * j + 4 * k) * (*(const f32x4*)(scp + 512 * j + 4 * k) + 1.0f); sh[j][k] = *(const f32x4*)(shp + 512 * j + 4 * k); } }
;         f32x4 xr[2][2][2][2]; u32x4 xb[2][2][2], yb[2][2][2];
;     ...
;         ELEM_LOAD(0, tok0);
.LBB0_95:
	s_ashr_i32 s1, s2, 4
	s_lshr_b32 s4, s1, 3
	s_bfe_u32 s10, s1, 0x30003
	s_mul_i32 s10, s10, 48
	s_and_b32 s4, s4, 0x1ffffff8
	s_add_i32 s10, s10, s4
	s_and_b32 s1, s1, 7
	s_or_b32 s1, s10, s1
	s_lshl_b32 s1, s1, 8
	v_sub_co_u32_e32 v2, vcc, s1, v211
	s_lshl_b32 s4, s2, 4
	v_readfirstlane_b32 s11, v2
	s_and_b32 s4, s4, 0xf0
	s_lshr_b32 s11, s11, 13
	s_and_b32 s0, s44, 0xf0
	s_or_b32 s4, s1, s4
	s_add_i32 s33, s11, 32
	s_lshr_b32 s34, s10, 3
	s_and_b64 s[10:11], vcc, exec
	s_cselect_b32 s10, s34, s33
	s_lshl_b32 s33, s10, 2
	s_add_u32 s10, s33, s3
	s_addc_u32 s11, 0, s35
	s_mul_i32 s34, s11, 0x6000
	v_mad_u64_u32 v[2:3], s[10:11], s10, v212, v[86:87]
	v_add_u32_e32 v3, s34, v3
	s_mov_b64 s[10:11], 0x5000
	v_lshl_add_u64 v[4:5], v[2:3], 0, s[10:11]
	s_movk_i32 s10, 0x5000
	v_add_co_u32_e32 v6, vcc, s10, v2
	s_mov_b64 s[10:11], 0x5800
	s_nop 0
	v_addc_co_u32_e32 v7, vcc, 0, v3, vcc
	v_lshl_add_u64 v[2:3], v[2:3], 0, s[10:11]
	v_readlane_b32 s10, v248, 63
	v_readlane_b32 s11, v246, 0
	s_or_b32 s10, s33, s10
	v_readlane_b32 s38, v248, 10
	v_mad_u64_u32 v[14:15], s[10:11], s10, v212, v[86:87]
	v_readlane_b32 s39, v248, 11
	s_mov_b64 s[10:11], 0x1000
	s_mov_b32 s5, s39
	global_load_dwordx4 v[50:53], v[6:7], off
	global_load_dwordx4 v[54:57], v[4:5], off offset:16
	global_load_dwordx4 v[58:61], v[88:89], off offset:16
	global_load_dwordx4 v[62:65], v[88:89], off
	v_lshl_add_u64 v[4:5], v[14:15], 0, s[10:11]
	s_mov_b64 s[10:11], 0x1800
	v_lshl_add_u64 v[10:11], v[14:15], 0, s[10:11]
	s_lshl_b64 s[10:11], s[4:5], 12
	s_waitcnt vmcnt(18)
	v_lshl_add_u64 v[22:23], v[92:93], 0, s[10:11]
	s_lshl_b64 s[10:11], s[4:5], 11
	s_or_b32 s4, s4, 1
	s_waitcnt vmcnt(16)
	v_lshl_add_u64 v[30:31], v[94:95], 0, s[10:11]
	s_lshl_b64 s[10:11], s[4:5], 12
	global_load_dwordx4 v[66:69], v[4:5], off offset:16
	v_add_co_u32_e32 v4, vcc, s83, v14
	s_waitcnt vmcnt(15)
	v_lshl_add_u64 v[38:39], v[92:93], 0, s[10:11]
	s_lshl_b64 s[10:11], s[4:5], 11
	v_addc_co_u32_e32 v5, vcc, 0, v15, vcc
	s_waitcnt vmcnt(13)
	v_lshl_add_u64 v[46:47], v[94:95], 0, s[10:11]
	global_load_dwordx4 v[70:73], v[4:5], off
	global_load_dwordx4 v[74:77], v[4:5], off offset:2048
	global_load_dwordx4 v[78:81], v[6:7], off offset:2048
	global_load_dwordx4 v[82:85], v[2:3], off offset:16
	global_load_dwordx4 v[110:113], v[88:89], off offset:2064
	global_load_dwordx4 v[106:109], v[88:89], off offset:2048
	global_load_dwordx4 v[114:117], v[90:91], off offset:16
	global_load_dwordx4 v[118:121], v[90:91], off
	s_nop 0
	global_load_dwordx4 v[2:5], v[14:15], off offset:16
	global_load_dwordx4 v[6:9], v[14:15], off
	global_load_dwordx4 v[126:129], v[90:91], off offset:2064
	global_load_dwordx4 v[122:125], v[90:91], off offset:2048
	global_load_dwordx4 v[130:133], v[10:11], off offset:16
	s_nop 0
	global_load_dwordx4 v[10:13], v[14:15], off offset:2064
	s_nop 0
	global_load_dwordx4 v[14:17], v[14:15], off offset:2048
	s_nop 0
	global_load_dwordx4 v[18:21], v[22:23], off
	s_nop 0
	global_load_dwordx4 v[22:25], v[22:23], off offset:1024
	s_nop 0
	global_load_dwordx4 v[26:29], v[30:31], off
	s_nop 0
	global_load_dwordx4 v[30:33], v[30:31], off offset:1024
	s_nop 0
	global_load_dwordx4 v[34:37], v[38:39], off
	s_nop 0
	global_load_dwordx4 v[38:41], v[38:39], off offset:1024
	s_nop 0
	global_load_dwordx4 v[42:45], v[46:47], off
	s_nop 0
	global_load_dwordx4 v[46:49], v[46:47], off offset:1024
	s_or_b32 s4, s1, s0
	s_lshl_b64 s[0:1], s[4:5], 12
	v_readlane_b32 s10, v248, 41
	s_add_u32 s10, s10, s0
	v_readlane_b32 s11, v248, 42
	s_addc_u32 s11, s11, s1
	v_writelane_b32 v248, s4, 10
	s_lshl_b64 s[38:39], s[4:5], 11
	s_add_u32 s38, s26, s38
	s_addc_u32 s39, s27, s39
	s_add_u32 s40, s24, s0
	s_mov_b32 s45, 0
	s_addc_u32 s41, s25, s1
	s_mov_b64 s[42:43], s[38:39]
	s_mov_b32 s6, 0x3a800000
	v_writelane_b32 v248, s5, 11
	s_waitcnt vmcnt(25)
	v_pk_mul_f32 v[100:101], v[56:57], v[60:61]
	s_waitcnt vmcnt(24)
	v_pk_mul_f32 v[96:97], v[52:53], v[64:65]
	v_pk_mul_f32 v[98:99], v[50:51], v[62:63]
	v_pk_mul_f32 v[102:103], v[54:55], v[58:59]
	s_waitcnt vmcnt(22)
	v_pk_add_f32 v[72:73], v[72:73], 1.0 op_sel_hi:[1,0]
	v_pk_add_f32 v[68:69], v[68:69], 1.0 op_sel_hi:[1,0]
	v_pk_add_f32 v[66:67], v[66:67], 1.0 op_sel_hi:[1,0]
	v_pk_add_f32 v[70:71], v[70:71], 1.0 op_sel_hi:[1,0]
	s_waitcnt vmcnt(21)
	v_pk_add_f32 v[76:77], v[76:77], 1.0 op_sel_hi:[1,0]
	v_pk_add_f32 v[74:75], v[74:75], 1.0 op_sel_hi:[1,0]
	s_waitcnt vmcnt(17)
	v_pk_mul_f32 v[104:105], v[80:81], v[108:109]
	v_pk_mul_f32 v[106:107], v[78:79], v[106:107]
	s_waitcnt vmcnt(10)
	v_pk_add_f32 v[50:51], v[132:133], 1.0 op_sel_hi:[1,0]
	v_pk_add_f32 v[52:53], v[130:131], 1.0 op_sel_hi:[1,0]
	v_pk_mul_f32 v[108:109], v[84:85], v[112:113]
	v_pk_mul_f32 v[110:111], v[82:83], v[110:111]
	v_pk_mul_f32 v[112:113], v[116:117], v[68:69]
	v_pk_mul_f32 v[114:115], v[114:115], v[66:67]
	v_pk_mul_f32 v[116:117], v[120:121], v[72:73]
	v_pk_mul_f32 v[118:119], v[118:119], v[70:71]
	v_pk_mul_f32 v[120:121], v[124:125], v[76:77]
	v_pk_mul_f32 v[122:123], v[122:123], v[74:75]
	v_pk_mul_f32 v[124:125], v[128:129], v[50:51]
	v_pk_mul_f32 v[126:127], v[126:127], v[52:53]
	s_branch .LBB0_97

; template <int x_mode_in>
; __device__ __forceinline__ void phase_elem(const Params& p, bool prev, bool has_y, int l_res, int jg, int ngi_res, int x_mode_out, bool write_h, int l_h, int jsh, int ngi_h) {
;     ...
;         const int pos = prev ? 383 - (b >> 4) : (b >> 4), pmo = 48 * ((pos & 63) >> 3) + 8 * (pos >> 6) + (pos & 7);
;         const int tok0 = pmo * 256 + (b & 15) * 16, s = seq_of(tok0);
;         f32x4 ar[2][2], ah[2][2], sh[2][2];
; #pragma unroll
;         for (int j = 0; j < 2; ++j)
; #pragma unroll
;             for (int k = 0; k < 2; ++k) { ar[j][k] = (f32x4){0.f, 0.f, 0.f, 0.f}; ah[j][k] = ar[j][k]; sh[j][k] = ar[j][k]; }
;         if (has_y) { const float* gp = mod + (((size_t)s * 4 + l_res) * 6 + jg) * 1024 + 8 * lane; const float* np = norm_g + (l_res * 4 + ngi_res) * 1024 + 8 * lane;
; #pragma unroll
;             for (int j = 0; j < 2; ++j)
; #pragma unroll
;                 for (int k = 0; k < 2; ++k) ar[j][k] = *(const f32x4*)(gp + 512 * j + 4 * k) * *(const f32x4*)(np + 512 * j + 4 * k); }
;         if (write_h) { const float* shp = mod + (((size_t)s * 4 + l_h) * 6 + jsh) * 1024 + 8 * lane; const float* scp = shp + 1024; const float* np = norm_g + (l_h * 4 + ngi_h) * 1024 + 8 * lane;
; #pragma unroll
;             for (int j = 0; j < 2; ++j)
; #pragma unroll
;                 for (int k = 0; k < 2; ++k) { ah[j][k] = *(const f32x4*)(np + 512 * j + 4 * k) * (*(const f32x4*)(scp + 512 * j + 4 * k) + 1.0f); sh[j][k] = *(const f32x4*)(shp + 512 * j + 4 * k); } }
;         f32x4 xr[2][2][2][2]; u32x4 xb[2][2][2], yb[2][2][2];
;     ...
;         ELEM_LOAD(0, tok0);
.LBB0_724:
	s_ashr_i32 s0, s7, 4
	s_lshr_b32 s10, s0, 3
	s_bfe_u32 s11, s0, 0x30003
	s_mul_i32 s11, s11, 48
	s_and_b32 s10, s10, 0x1ffffff8
	s_add_i32 s11, s11, s10
	s_and_b32 s0, s0, 7
	s_or_b32 s0, s11, s0
	s_lshl_b32 s21, s0, 8
	s_waitcnt vmcnt(15)
	v_sub_co_u32_e32 v0, vcc, s21, v65
	s_lshl_b32 s0, s7, 4
	v_readfirstlane_b32 s10, v0
	s_and_b32 s0, s0, 0xf0
	s_lshr_b32 s10, s10, 13
	s_and_b32 s20, s14, 0xf0
	s_or_b32 s0, s21, s0
	s_add_i32 s12, s10, 32
	s_lshr_b32 s13, s11, 3
	s_and_b64 s[10:11], vcc, exec
	s_cselect_b32 s10, s13, s12
	s_lshl_b32 s10, s10, 2
	s_or_b32 s10, s10, 3
	s_waitcnt vmcnt(11)
	v_mad_u64_u32 v[16:17], s[10:11], s10, v117, v[66:67]
	v_add_co_u32_e32 v82, vcc, s15, v16
	s_lshl_b64 s[10:11], s[0:1], 12
	s_nop 0
	v_addc_co_u32_e32 v83, vcc, 0, v17, vcc
	v_lshl_add_u64 v[0:1], v[16:17], 0, s[2:3]
	s_lshl_b64 s[12:13], s[0:1], 11
	v_lshl_add_u64 v[18:19], v[70:71], 0, s[10:11]
	global_load_dwordx4 v[32:35], v[68:69], off
	global_load_dwordx4 v[36:39], v[68:69], off offset:16
	global_load_dwordx4 v[40:43], v[82:83], off
	global_load_dwordx4 v[44:47], v[0:1], off offset:16
	global_load_dwordx4 v[48:51], v[68:69], off offset:2064
	global_load_dwordx4 v[52:55], v[68:69], off offset:2048
	s_waitcnt vmcnt(16)
	v_lshl_add_u64 v[20:21], v[72:73], 0, s[12:13]
	global_load_dwordx4 v[0:3], v[18:19], off
	global_load_dwordx4 v[4:7], v[18:19], off offset:1024
	global_load_dwordx4 v[8:11], v[20:21], off
	global_load_dwordx4 v[12:15], v[20:21], off offset:1024
	s_or_b32 s0, s0, 1
	s_lshl_b64 s[10:11], s[0:1], 12
	s_lshl_b64 s[12:13], s[0:1], 11
	v_lshl_add_u64 v[84:85], v[70:71], 0, s[10:11]
	v_lshl_add_u64 v[86:87], v[72:73], 0, s[12:13]
	v_lshl_add_u64 v[88:89], v[16:17], 0, s[4:5]
	global_load_dwordx4 v[56:59], v[82:83], off offset:2048
	global_load_dwordx4 v[60:63], v[88:89], off offset:16
	global_load_dwordx4 v[16:19], v[84:85], off
	global_load_dwordx4 v[20:23], v[84:85], off offset:1024
	global_load_dwordx4 v[24:27], v[86:87], off
	global_load_dwordx4 v[28:31], v[86:87], off offset:1024
	s_or_b32 s0, s21, s20
	s_lshl_b64 s[12:13], s[0:1], 12
	s_lshl_b64 s[20:21], s[0:1], 11
	s_mov_b64 s[10:11], s[24:25]
	v_mov_b32_e32 v83, s13
	v_or_b32_e32 v82, s12, v64
	v_mov_b32_e32 v85, s13
	v_or_b32_e32 v84, s12, v76
	v_lshl_add_u64 v[86:87], v[78:79], 0, s[20:21]
	v_mov_b32_e32 v89, s13
	v_or_b32_e32 v88, s12, v74
	s_mov_b32 s20, 0
	s_waitcnt vmcnt(13)
	v_pk_mul_f32 v[90:91], v[42:43], v[34:35]
	v_pk_mul_f32 v[92:93], v[40:41], v[32:33]
	s_waitcnt vmcnt(12)
	v_pk_mul_f32 v[94:95], v[46:47], v[38:39]
	v_pk_mul_f32 v[96:97], v[44:45], v[36:37]
	s_waitcnt vmcnt(5)
	v_pk_mul_f32 v[98:99], v[58:59], v[54:55]
	v_pk_mul_f32 v[100:101], v[56:57], v[52:53]
	s_waitcnt vmcnt(4)
	v_pk_mul_f32 v[102:103], v[62:63], v[50:51]
	v_pk_mul_f32 v[104:105], v[60:61], v[48:49]
	s_branch .LBB0_726
